# ff1 epilogue: store addresses formed as one per-lane base plus scalar constants; dead 64-bit address arithmetic removed
# baseline (speedup 1.0000x reference)
.LBB0_1263:
	s_add_u32 s10, s46, 0xfffc0080
	s_addc_u32 s11, s47, -1
	s_add_i32 s69, 0, 0x10000
	v_add_u32_e32 v124, s69, v203
	ds_read_b128 v[112:115], v124
	ds_read_b128 v[116:119], v124 offset:1024
	ds_read_b128 v[120:123], v124 offset:2048
	ds_read_b128 v[124:127], v124 offset:3072
	s_cmp_eq_u32 s39, 12
	s_cselect_b32 s13, s16, s11
	s_cselect_b32 s12, s17, s10
	s_cselect_b32 s11, s20, s31
	s_cselect_b32 s10, s21, s27
	v_lshl_add_u64 v[208:209], s[46:47], 0, v[188:189]
	s_add_i32 m0, s54, 0xc000
	ds_read_b128 v[128:131], v206
	ds_read_b128 v[132:135], v206 offset:1024
	ds_read_b128 v[136:139], v206 offset:2048
	ds_read_b128 v[140:143], v206 offset:3072
	ds_read_b128 v[156:159], v206 offset:4096
	ds_read_b128 v[164:167], v206 offset:5120
	ds_read_b128 v[192:195], v206 offset:6144
	ds_read_b128 v[196:199], v206 offset:7168
	global_load_lds_dwordx4 v[208:209], off
	v_lshl_add_u64 v[208:209], s[46:47], 0, v[190:191]
	s_add_i32 m0, s54, 0xe000
	s_nop 0
	global_load_lds_dwordx4 v[208:209], off
	s_waitcnt lgkmcnt(8)
	s_barrier
	s_waitcnt lgkmcnt(0)
	s_setprio 1
	s_waitcnt lgkmcnt(0)
	v_mfma_f32_16x16x32_bf16 v[160:163], v[112:115], v[128:131], v[160:163]
	v_mfma_f32_16x16x32_bf16 v[152:155], v[120:123], v[128:131], v[152:155]
	v_mfma_f32_16x16x32_bf16 v[148:151], v[112:115], v[136:139], v[148:151]
	v_mfma_f32_16x16x32_bf16 v[144:147], v[120:123], v[136:139], v[144:147]
	v_mfma_f32_16x16x32_bf16 v[108:111], v[112:115], v[156:159], v[108:111]
	v_mfma_f32_16x16x32_bf16 v[104:107], v[120:123], v[156:159], v[104:107]
	v_mfma_f32_16x16x32_bf16 v[100:103], v[112:115], v[192:195], v[100:103]
	v_mfma_f32_16x16x32_bf16 v[96:99], v[120:123], v[192:195], v[96:99]
	v_mfma_f32_16x16x32_bf16 v[160:163], v[116:119], v[132:135], v[160:163]
	v_mfma_f32_16x16x32_bf16 v[152:155], v[124:127], v[132:135], v[152:155]
	v_mfma_f32_16x16x32_bf16 v[148:151], v[116:119], v[140:143], v[148:151]
	v_mfma_f32_16x16x32_bf16 v[144:147], v[124:127], v[140:143], v[144:147]
	v_mfma_f32_16x16x32_bf16 v[108:111], v[116:119], v[164:167], v[108:111]
	v_mfma_f32_16x16x32_bf16 v[104:107], v[124:127], v[164:167], v[104:107]
	v_mfma_f32_16x16x32_bf16 v[100:103], v[116:119], v[196:199], v[100:103]
	v_mfma_f32_16x16x32_bf16 v[96:99], v[124:127], v[196:199], v[96:99]
	s_setprio 0
	s_barrier
	s_add_i32 s78, 0, 0x14000
	s_add_i32 s69, s69, s45
	v_add_u32_e32 v168, s78, v203
	v_lshl_add_u64 v[224:225], s[10:11], 0, v[174:175]
	s_mov_b32 m0, s69
	ds_read_b128 v[208:211], v168
	ds_read_b128 v[212:215], v168 offset:1024
	ds_read_b128 v[216:219], v168 offset:2048
	ds_read_b128 v[220:223], v168 offset:3072
	global_load_lds_dwordx4 v[224:225], off
	v_lshl_add_u64 v[226:227], s[10:11], 0, v[182:183]
	s_add_i32 m0, s69, 0x2000
	s_nop 0
	global_load_lds_dwordx4 v[226:227], off
	s_barrier
	s_waitcnt lgkmcnt(0)
	s_setprio 1
	s_waitcnt lgkmcnt(0)
	v_mfma_f32_16x16x32_bf16 v[92:95], v[208:211], v[128:131], v[92:95]
	v_mfma_f32_16x16x32_bf16 v[88:91], v[216:219], v[128:131], v[88:91]
	v_mfma_f32_16x16x32_bf16 v[84:87], v[208:211], v[136:139], v[84:87]
	v_mfma_f32_16x16x32_bf16 v[80:83], v[216:219], v[136:139], v[80:83]
	v_mfma_f32_16x16x32_bf16 v[76:79], v[208:211], v[156:159], v[76:79]
	v_mfma_f32_16x16x32_bf16 v[72:75], v[216:219], v[156:159], v[72:75]
	v_mfma_f32_16x16x32_bf16 v[68:71], v[208:211], v[192:195], v[68:71]
	v_mfma_f32_16x16x32_bf16 v[64:67], v[216:219], v[192:195], v[64:67]
	v_mfma_f32_16x16x32_bf16 v[92:95], v[212:215], v[132:135], v[92:95]
	v_mfma_f32_16x16x32_bf16 v[88:91], v[220:223], v[132:135], v[88:91]
	v_mfma_f32_16x16x32_bf16 v[84:87], v[212:215], v[140:143], v[84:87]
	v_mfma_f32_16x16x32_bf16 v[80:83], v[220:223], v[140:143], v[80:83]
	v_mfma_f32_16x16x32_bf16 v[76:79], v[212:215], v[164:167], v[76:79]
	v_mfma_f32_16x16x32_bf16 v[72:75], v[220:223], v[164:167], v[72:75]
	v_mfma_f32_16x16x32_bf16 v[68:71], v[212:215], v[196:199], v[68:71]
	v_mfma_f32_16x16x32_bf16 v[64:67], v[220:223], v[196:199], v[64:67]
	s_setprio 0
	s_mov_b32 m0, s54
	v_lshl_add_u64 v[228:229], s[12:13], 0, v[186:187]
	s_barrier
	ds_read_b128 v[128:131], v206 offset:16384
	ds_read_b128 v[132:135], v206 offset:17408
	ds_read_b128 v[136:139], v206 offset:18432
	ds_read_b128 v[140:143], v206 offset:19456
	ds_read_b128 v[156:159], v206 offset:20480
	ds_read_b128 v[164:167], v206 offset:21504
	ds_read_b128 v[192:195], v206 offset:22528
	ds_read_b128 v[196:199], v206 offset:23552
	global_load_lds_dwordx4 v[228:229], off
	v_lshl_add_u64 v[230:231], s[12:13], 0, v[184:185]
	s_mov_b32 m0, s55
	s_nop 0
	global_load_lds_dwordx4 v[230:231], off
	s_barrier
	s_waitcnt lgkmcnt(0)
	s_setprio 1
	s_waitcnt lgkmcnt(0)
	v_mfma_f32_16x16x32_bf16 v[60:63], v[112:115], v[128:131], v[60:63]
	v_mfma_f32_16x16x32_bf16 v[56:59], v[120:123], v[128:131], v[56:59]
	v_mfma_f32_16x16x32_bf16 v[52:55], v[112:115], v[136:139], v[52:55]
	v_mfma_f32_16x16x32_bf16 v[48:51], v[120:123], v[136:139], v[48:51]
	v_mfma_f32_16x16x32_bf16 v[44:47], v[112:115], v[156:159], v[44:47]
	v_mfma_f32_16x16x32_bf16 v[40:43], v[120:123], v[156:159], v[40:43]
	v_mfma_f32_16x16x32_bf16 v[36:39], v[112:115], v[192:195], v[36:39]
	v_mfma_f32_16x16x32_bf16 v[32:35], v[120:123], v[192:195], v[32:35]
	v_mfma_f32_16x16x32_bf16 v[60:63], v[116:119], v[132:135], v[60:63]
	v_mfma_f32_16x16x32_bf16 v[56:59], v[124:127], v[132:135], v[56:59]
	v_mfma_f32_16x16x32_bf16 v[52:55], v[116:119], v[140:143], v[52:55]
	v_mfma_f32_16x16x32_bf16 v[48:51], v[124:127], v[140:143], v[48:51]
	v_mfma_f32_16x16x32_bf16 v[44:47], v[116:119], v[164:167], v[44:47]
	v_mfma_f32_16x16x32_bf16 v[40:43], v[124:127], v[164:167], v[40:43]
	v_mfma_f32_16x16x32_bf16 v[36:39], v[116:119], v[196:199], v[36:39]
	v_mfma_f32_16x16x32_bf16 v[32:35], v[124:127], v[196:199], v[32:35]
	s_setprio 0
	s_barrier
	s_add_u32 s76, s10, 0x40000
	s_addc_u32 s77, s11, 0
	s_add_i32 s69, s78, s45
	v_lshl_add_u64 v[112:113], s[76:77], 0, v[174:175]
	s_mov_b32 m0, s69
	s_nop 0
	global_load_lds_dwordx4 v[112:113], off
	v_lshl_add_u64 v[112:113], s[76:77], 0, v[182:183]
	s_add_i32 m0, s69, 0x2000
	s_nop 0
	global_load_lds_dwordx4 v[112:113], off
	s_waitcnt vmcnt(6)
	s_barrier
	s_setprio 1
	v_mfma_f32_16x16x32_bf16 v[28:31], v[208:211], v[128:131], v[28:31]
	v_mfma_f32_16x16x32_bf16 v[24:27], v[216:219], v[128:131], v[24:27]
	v_mfma_f32_16x16x32_bf16 v[20:23], v[208:211], v[136:139], v[20:23]
	v_mfma_f32_16x16x32_bf16 v[16:19], v[216:219], v[136:139], v[16:19]
	v_mfma_f32_16x16x32_bf16 v[12:15], v[208:211], v[156:159], v[12:15]
	v_mfma_f32_16x16x32_bf16 v[8:11], v[216:219], v[156:159], v[8:11]
	v_mfma_f32_16x16x32_bf16 v[4:7], v[208:211], v[192:195], v[4:7]
	v_mfma_f32_16x16x32_bf16 v[0:3], v[216:219], v[192:195], v[0:3]
	v_mfma_f32_16x16x32_bf16 v[28:31], v[212:215], v[132:135], v[28:31]
	v_mfma_f32_16x16x32_bf16 v[24:27], v[220:223], v[132:135], v[24:27]
	v_mfma_f32_16x16x32_bf16 v[20:23], v[212:215], v[140:143], v[20:23]
	v_mfma_f32_16x16x32_bf16 v[16:19], v[220:223], v[140:143], v[16:19]
	v_mfma_f32_16x16x32_bf16 v[12:15], v[212:215], v[164:167], v[12:15]
	v_mfma_f32_16x16x32_bf16 v[8:11], v[220:223], v[164:167], v[8:11]
	v_mfma_f32_16x16x32_bf16 v[4:7], v[212:215], v[196:199], v[4:7]
	v_mfma_f32_16x16x32_bf16 v[0:3], v[220:223], v[196:199], v[0:3]
	s_setprio 0
	s_add_i32 s69, 0, 0x18000
	v_add_u32_e32 v124, s69, v203
	s_barrier
	ds_read_b128 v[112:115], v124
	ds_read_b128 v[116:119], v124 offset:1024
	ds_read_b128 v[120:123], v124 offset:2048
	ds_read_b128 v[124:127], v124 offset:3072
	s_add_u32 s12, s12, 0x40000
	s_addc_u32 s13, s13, 0
	s_mov_b32 m0, s58
	v_lshl_add_u64 v[208:209], s[12:13], 0, v[186:187]
	ds_read_b128 v[128:131], v206 offset:32768
	ds_read_b128 v[132:135], v206 offset:33792
	ds_read_b128 v[136:139], v206 offset:34816
	ds_read_b128 v[140:143], v206 offset:35840
	ds_read_b128 v[156:159], v206 offset:36864
	ds_read_b128 v[164:167], v206 offset:37888
	ds_read_b128 v[192:195], v206 offset:38912
	ds_read_b128 v[196:199], v206 offset:39936
	global_load_lds_dwordx4 v[208:209], off
	v_lshl_add_u64 v[208:209], s[12:13], 0, v[184:185]
	s_mov_b32 m0, s59
	s_nop 0
	global_load_lds_dwordx4 v[208:209], off
	s_waitcnt lgkmcnt(8)
	s_barrier
	s_waitcnt lgkmcnt(0)
	s_setprio 1
	s_waitcnt lgkmcnt(0)
	v_mfma_f32_16x16x32_bf16 v[160:163], v[112:115], v[128:131], v[160:163]
	v_mfma_f32_16x16x32_bf16 v[152:155], v[120:123], v[128:131], v[152:155]
	v_mfma_f32_16x16x32_bf16 v[148:151], v[112:115], v[136:139], v[148:151]
	v_mfma_f32_16x16x32_bf16 v[144:147], v[120:123], v[136:139], v[144:147]
	v_mfma_f32_16x16x32_bf16 v[108:111], v[112:115], v[156:159], v[108:111]
	v_mfma_f32_16x16x32_bf16 v[104:107], v[120:123], v[156:159], v[104:107]
	v_mfma_f32_16x16x32_bf16 v[100:103], v[112:115], v[192:195], v[100:103]
	v_mfma_f32_16x16x32_bf16 v[96:99], v[120:123], v[192:195], v[96:99]
	v_mfma_f32_16x16x32_bf16 v[160:163], v[116:119], v[132:135], v[160:163]
	v_mfma_f32_16x16x32_bf16 v[152:155], v[124:127], v[132:135], v[152:155]
	v_mfma_f32_16x16x32_bf16 v[148:151], v[116:119], v[140:143], v[148:151]
	v_mfma_f32_16x16x32_bf16 v[144:147], v[124:127], v[140:143], v[144:147]
	v_mfma_f32_16x16x32_bf16 v[108:111], v[116:119], v[164:167], v[108:111]
	v_mfma_f32_16x16x32_bf16 v[104:107], v[124:127], v[164:167], v[104:107]
	v_mfma_f32_16x16x32_bf16 v[100:103], v[116:119], v[196:199], v[100:103]
	v_mfma_f32_16x16x32_bf16 v[96:99], v[124:127], v[196:199], v[96:99]
	s_setprio 0
	s_barrier
	s_add_i32 s12, 0, 0x1c000
	s_add_i32 s13, s69, s45
	v_add_u32_e32 v168, s12, v203
	v_lshl_add_u64 v[224:225], v[224:225], 0, s[8:9]
	s_mov_b32 m0, s13
	ds_read_b128 v[208:211], v168
	ds_read_b128 v[212:215], v168 offset:1024
	ds_read_b128 v[216:219], v168 offset:2048
	ds_read_b128 v[220:223], v168 offset:3072
	global_load_lds_dwordx4 v[224:225], off
	v_lshl_add_u64 v[224:225], v[226:227], 0, s[8:9]
	s_add_i32 m0, s13, 0x2000
	s_nop 0
	global_load_lds_dwordx4 v[224:225], off
	s_barrier
	s_waitcnt lgkmcnt(0)
	s_setprio 1
	s_waitcnt lgkmcnt(0)
	v_mfma_f32_16x16x32_bf16 v[92:95], v[208:211], v[128:131], v[92:95]
	v_mfma_f32_16x16x32_bf16 v[88:91], v[216:219], v[128:131], v[88:91]
	v_mfma_f32_16x16x32_bf16 v[84:87], v[208:211], v[136:139], v[84:87]
	v_mfma_f32_16x16x32_bf16 v[80:83], v[216:219], v[136:139], v[80:83]
	v_mfma_f32_16x16x32_bf16 v[76:79], v[208:211], v[156:159], v[76:79]
	v_mfma_f32_16x16x32_bf16 v[72:75], v[216:219], v[156:159], v[72:75]
	v_mfma_f32_16x16x32_bf16 v[68:71], v[208:211], v[192:195], v[68:71]
	v_mfma_f32_16x16x32_bf16 v[64:67], v[216:219], v[192:195], v[64:67]
	v_mfma_f32_16x16x32_bf16 v[92:95], v[212:215], v[132:135], v[92:95]
	v_mfma_f32_16x16x32_bf16 v[88:91], v[220:223], v[132:135], v[88:91]
	v_mfma_f32_16x16x32_bf16 v[84:87], v[212:215], v[140:143], v[84:87]
	v_mfma_f32_16x16x32_bf16 v[80:83], v[220:223], v[140:143], v[80:83]
	v_mfma_f32_16x16x32_bf16 v[76:79], v[212:215], v[164:167], v[76:79]
	v_mfma_f32_16x16x32_bf16 v[72:75], v[220:223], v[164:167], v[72:75]
	v_mfma_f32_16x16x32_bf16 v[68:71], v[212:215], v[196:199], v[68:71]
	v_mfma_f32_16x16x32_bf16 v[64:67], v[220:223], v[196:199], v[64:67]
	s_setprio 0
	s_mov_b32 m0, s62
	v_lshl_add_u64 v[224:225], v[228:229], 0, s[8:9]
	s_barrier
	ds_read_b128 v[128:131], v206 offset:49152
	ds_read_b128 v[132:135], v206 offset:50176
	ds_read_b128 v[136:139], v206 offset:51200
	ds_read_b128 v[140:143], v206 offset:52224
	ds_read_b128 v[156:159], v206 offset:53248
	ds_read_b128 v[164:167], v206 offset:54272
	ds_read_b128 v[192:195], v206 offset:55296
	ds_read_b128 v[196:199], v206 offset:56320
	global_load_lds_dwordx4 v[224:225], off
	v_lshl_add_u64 v[224:225], v[230:231], 0, s[8:9]
	s_mov_b32 m0, s63
	s_nop 0
	global_load_lds_dwordx4 v[224:225], off
	s_barrier
	s_waitcnt lgkmcnt(0)
	s_setprio 1
	s_waitcnt lgkmcnt(0)
	v_mfma_f32_16x16x32_bf16 v[60:63], v[112:115], v[128:131], v[60:63]
	v_mfma_f32_16x16x32_bf16 v[56:59], v[120:123], v[128:131], v[56:59]
	v_mfma_f32_16x16x32_bf16 v[52:55], v[112:115], v[136:139], v[52:55]
	v_mfma_f32_16x16x32_bf16 v[48:51], v[120:123], v[136:139], v[48:51]
	v_mfma_f32_16x16x32_bf16 v[44:47], v[112:115], v[156:159], v[44:47]
	v_mfma_f32_16x16x32_bf16 v[40:43], v[120:123], v[156:159], v[40:43]
	v_mfma_f32_16x16x32_bf16 v[36:39], v[112:115], v[192:195], v[36:39]
	v_mfma_f32_16x16x32_bf16 v[32:35], v[120:123], v[192:195], v[32:35]
	v_mfma_f32_16x16x32_bf16 v[60:63], v[116:119], v[132:135], v[60:63]
	v_mfma_f32_16x16x32_bf16 v[56:59], v[124:127], v[132:135], v[56:59]
	v_mfma_f32_16x16x32_bf16 v[52:55], v[116:119], v[140:143], v[52:55]
	v_mfma_f32_16x16x32_bf16 v[48:51], v[124:127], v[140:143], v[48:51]
	v_mfma_f32_16x16x32_bf16 v[44:47], v[116:119], v[164:167], v[44:47]
	v_mfma_f32_16x16x32_bf16 v[40:43], v[124:127], v[164:167], v[40:43]
	v_mfma_f32_16x16x32_bf16 v[36:39], v[116:119], v[196:199], v[36:39]
	v_mfma_f32_16x16x32_bf16 v[32:35], v[124:127], v[196:199], v[32:35]
	s_setprio 0
	s_barrier
	s_add_u32 s10, s10, 0x40080
	s_addc_u32 s11, s11, 0
	s_add_i32 s12, s12, s45
	v_lshl_add_u64 v[112:113], s[10:11], 0, v[174:175]
	s_mov_b32 m0, s12
	s_nop 0
	global_load_lds_dwordx4 v[112:113], off
	v_lshl_add_u64 v[112:113], s[10:11], 0, v[182:183]
	s_add_i32 m0, s12, 0x2000
	s_nop 0
	global_load_lds_dwordx4 v[112:113], off
	s_waitcnt vmcnt(6)
	s_barrier
	s_setprio 1
	v_mfma_f32_16x16x32_bf16 v[28:31], v[208:211], v[128:131], v[28:31]
	v_mfma_f32_16x16x32_bf16 v[24:27], v[216:219], v[128:131], v[24:27]
	v_mfma_f32_16x16x32_bf16 v[20:23], v[208:211], v[136:139], v[20:23]
	v_mfma_f32_16x16x32_bf16 v[16:19], v[216:219], v[136:139], v[16:19]
	v_mfma_f32_16x16x32_bf16 v[12:15], v[208:211], v[156:159], v[12:15]
	v_mfma_f32_16x16x32_bf16 v[8:11], v[216:219], v[156:159], v[8:11]
	v_mfma_f32_16x16x32_bf16 v[4:7], v[208:211], v[192:195], v[4:7]
	v_mfma_f32_16x16x32_bf16 v[0:3], v[216:219], v[192:195], v[0:3]
	v_mfma_f32_16x16x32_bf16 v[28:31], v[212:215], v[132:135], v[28:31]
	v_mfma_f32_16x16x32_bf16 v[24:27], v[220:223], v[132:135], v[24:27]
	v_mfma_f32_16x16x32_bf16 v[20:23], v[212:215], v[140:143], v[20:23]
	v_mfma_f32_16x16x32_bf16 v[16:19], v[220:223], v[140:143], v[16:19]
	v_mfma_f32_16x16x32_bf16 v[12:15], v[212:215], v[164:167], v[12:15]
	v_mfma_f32_16x16x32_bf16 v[8:11], v[220:223], v[164:167], v[8:11]
	v_mfma_f32_16x16x32_bf16 v[4:7], v[212:215], v[196:199], v[4:7]
	v_mfma_f32_16x16x32_bf16 v[0:3], v[220:223], v[196:199], v[0:3]
	s_setprio 0
	s_add_i32 s39, s39, 2
	s_add_u32 s46, s46, 0x100
	s_addc_u32 s47, s47, 0
	s_add_u32 s27, s27, 0x100
	s_addc_u32 s31, s31, 0
	s_cmp_gt_u32 s39, 13
	s_barrier
	s_cbranch_scc0 .LBB0_1263
	s_mov_b32 s101, 0
	v_lshrrev_b32_e32 v226, 2, v237
	v_and_b32_e32 v227, 15, v237
	v_sub_u32_e32 v226, v226, v227
	v_lshlrev_b32_e32 v226, 13, v226
	v_and_b32_e32 v227, 3, v237
	v_lshrrev_b32_e32 v225, 4, v237
	v_sub_u32_e32 v227, v227, v225
	v_lshl_add_u32 v226, v227, 4, v226
	v_ashrrev_i32_e32 v227, 31, v226
	v_and_b32_e32 v225, 3, v237
	v_lshlrev_b32_e32 v225, 6, v225
	v_and_b32_e32 v224, 60, v237
	v_or_b32_e32 v224, v224, v225
	s_mov_b64 s[10:11], s[0:1]
	s_load_dwordx2 s[10:11], s[10:11], 0xd0
	s_mov_b32 s12, s44
	s_lshl_b32 s12, s12, 12
	s_ashr_i32 s13, s12, 31
	s_lshl_b64 s[12:13], s[12:13], 2
	s_waitcnt lgkmcnt(0)
	s_add_u32 s12, s10, s12
	v_lshl_or_b32 v192, s26, 8, v205
	s_addc_u32 s13, s11, s13
	v_ashrrev_i32_e32 v193, 31, v192
	v_lshl_add_u64 v[112:113], v[192:193], 2, s[12:13]
	s_mov_b64 s[12:13], 0xef8e000
	v_lshl_add_u64 v[116:117], v[112:113], 0, s[12:13]
	s_mov_b32 s12, 0xef8e000
	v_add_co_u32_e32 v114, vcc, s12, v112
	s_mov_b64 s[12:13], 0xef96000
	s_nop 0
	v_addc_co_u32_e32 v115, vcc, 0, v113, vcc
	v_lshl_add_u64 v[124:125], v[112:113], 0, s[12:13]
	s_mov_b32 s12, 0xef96000
	global_load_dwordx4 v[128:131], v[114:115], off
	global_load_dwordx4 v[132:135], v[116:117], off offset:16
	v_add_co_u32_e32 v112, vcc, s12, v112
	v_lshl_add_u32 v207, s25, 11, v204
	s_nop 0
	v_addc_co_u32_e32 v113, vcc, 0, v113, vcc
	global_load_dwordx4 v[136:139], v[112:113], off
	global_load_dwordx4 v[140:143], v[124:125], off offset:16
	s_nop 0
	global_load_dwordx4 v[112:115], v[116:117], off offset:528
	global_load_dwordx4 v[120:123], v[116:117], off offset:512
	s_nop 0
	global_load_dwordx4 v[116:119], v[124:125], off offset:528
	s_nop 0
	global_load_dwordx4 v[124:127], v[124:125], off offset:512
	ds_read2_b64 v[164:167], v207 offset1:16
	ds_read2_b64 v[156:159], v207 offset0:32 offset1:48
	s_add_u32 s46, s10, 0x6a80000
	v_lshl_add_u32 v198, s24, 8, v178
	s_addc_u32 s47, s11, 0
	v_ashrrev_i32_e32 v199, 31, v198
	v_or_b32_e32 v196, 0x80, v192
	v_lshl_add_u64 v[192:193], v[192:193], 1, s[46:47]
	v_ashrrev_i32_e32 v197, 31, v196
	s_mov_b64 s[10:11], 0x100000
	s_and_b64 vcc, exec, s[28:29]
	s_mov_b32 s26, s30
	s_mov_b32 s24, s38
	s_mov_b64 s[12:13], s[40:41]
	s_mov_b32 s25, s68
	s_waitcnt vmcnt(0)
	v_xor_b32_e32 v195, 0x80000000, v131
	v_xor_b32_e32 v194, 0x80000000, v130
	s_waitcnt lgkmcnt(1)
	v_pk_fma_f32 v[130:131], v[194:195], v[164:165], v[162:163] op_sel_hi:[1,0,1]
	v_pk_fma_f32 v[160:161], v[128:129], v[164:165], v[160:161] op_sel_hi:[1,0,1] neg_lo:[1,0,0] neg_hi:[1,0,0]
	v_pk_fma_f32 v[152:153], v[132:133], v[164:165], v[152:153] op_sel_hi:[1,0,1] neg_lo:[1,0,0] neg_hi:[1,0,0]
	v_pk_fma_f32 v[148:149], v[128:129], v[166:167], v[148:149] op_sel_hi:[1,0,1] neg_lo:[1,0,0] neg_hi:[1,0,0]
	v_pk_fma_f32 v[130:131], v[164:165], v[130:131], v[138:139] op_sel:[1,0,0]
	v_pk_fma_f32 v[160:161], v[164:165], v[160:161], v[136:137] op_sel:[1,0,0]
	v_max_f32_e32 v130, 0, v130
	v_max_f32_e32 v131, 0, v131
	v_pk_mul_f32 v[162:163], v[130:131], v[130:131]
	v_xor_b32_e32 v131, 0x80000000, v135
	v_xor_b32_e32 v130, 0x80000000, v134
	v_pk_fma_f32 v[134:135], v[130:131], v[164:165], v[154:155] op_sel_hi:[1,0,1]
	v_pk_fma_f32 v[152:153], v[164:165], v[152:153], v[140:141] op_sel:[1,0,0]
	v_pk_fma_f32 v[134:135], v[164:165], v[134:135], v[142:143] op_sel:[1,0,0]
	v_max_f32_e32 v160, 0, v160
	v_max_f32_e32 v134, 0, v134
	v_max_f32_e32 v135, 0, v135
	v_max_f32_e32 v161, 0, v161
	v_max_f32_e32 v152, 0, v152
	v_max_f32_e32 v153, 0, v153
	v_pk_mul_f32 v[208:209], v[134:135], v[134:135]
	v_lshlrev_b64 v[134:135], 13, v[198:199]
	v_pk_fma_f32 v[146:147], v[130:131], v[166:167], v[146:147] op_sel_hi:[1,0,1]
	v_pk_fma_f32 v[144:145], v[132:133], v[166:167], v[144:145] op_sel_hi:[1,0,1] neg_lo:[1,0,0] neg_hi:[1,0,0]
	v_pk_mul_f32 v[160:161], v[160:161], v[160:161]
	v_pk_mul_f32 v[154:155], v[152:153], v[152:153]
	v_lshl_add_u64 v[210:211], v[192:193], 0, v[134:135]
	v_cvt_pk_bf16_f32 v152, v160, v161
	v_cvt_pk_bf16_f32 v153, v162, v163
	v_pk_fma_f32 v[150:151], v[194:195], v[166:167], v[150:151] op_sel_hi:[1,0,1]
	v_pk_fma_f32 v[148:149], v[166:167], v[148:149], v[136:137] op_sel:[1,0,0]
	v_pk_fma_f32 v[146:147], v[166:167], v[146:147], v[142:143] op_sel:[1,0,0]
	v_pk_fma_f32 v[144:145], v[166:167], v[144:145], v[140:141] op_sel:[1,0,0]
	v_cvt_pk_bf16_f32 v154, v154, v155
	v_cvt_pk_bf16_f32 v155, v208, v209
	ds_bpermute_b32 v212, v224, v152
	ds_bpermute_b32 v213, v224, v153
	ds_bpermute_b32 v214, v224, v154
	ds_bpermute_b32 v215, v224, v155
	v_lshl_add_u64 v[220:221], v[210:211], 0, v[226:227]
	v_mov_b64_e32 v[228:229], v[220:221]
	v_pk_fma_f32 v[150:151], v[166:167], v[150:151], v[138:139] op_sel:[1,0,0]
	v_max_f32_e32 v144, 0, v144
	v_max_f32_e32 v152, 0, v148
	v_max_f32_e32 v153, 0, v149
	v_max_f32_e32 v145, 0, v145
	v_max_f32_e32 v146, 0, v146
	v_max_f32_e32 v147, 0, v147
	v_max_f32_e32 v148, 0, v150
	v_max_f32_e32 v149, 0, v151
	v_pk_mul_f32 v[150:151], v[152:153], v[152:153]
	v_pk_mul_f32 v[146:147], v[146:147], v[146:147]
	v_pk_mul_f32 v[152:153], v[144:145], v[144:145]
	v_pk_mul_f32 v[148:149], v[148:149], v[148:149]
	v_cvt_pk_bf16_f32 v150, v150, v151
	v_cvt_pk_bf16_f32 v151, v148, v149
	v_cvt_pk_bf16_f32 v152, v152, v153
	v_cvt_pk_bf16_f32 v153, v146, v147
	s_waitcnt lgkmcnt(0)
	v_pk_fma_f32 v[108:109], v[128:129], v[156:157], v[108:109] op_sel_hi:[1,0,1] neg_lo:[1,0,0] neg_hi:[1,0,0]
	v_pk_fma_f32 v[106:107], v[130:131], v[156:157], v[106:107] op_sel_hi:[1,0,1]
	v_pk_fma_f32 v[104:105], v[132:133], v[156:157], v[104:105] op_sel_hi:[1,0,1] neg_lo:[1,0,0] neg_hi:[1,0,0]
	v_pk_fma_f32 v[110:111], v[194:195], v[156:157], v[110:111] op_sel_hi:[1,0,1]
	v_pk_fma_f32 v[108:109], v[156:157], v[108:109], v[136:137] op_sel:[1,0,0]
	v_pk_fma_f32 v[106:107], v[156:157], v[106:107], v[142:143] op_sel:[1,0,0]
	v_pk_fma_f32 v[104:105], v[156:157], v[104:105], v[140:141] op_sel:[1,0,0]
	v_pk_fma_f32 v[110:111], v[156:157], v[110:111], v[138:139] op_sel:[1,0,0]
	v_max_f32_e32 v108, 0, v108
	v_max_f32_e32 v109, 0, v109
	v_max_f32_e32 v104, 0, v104
	v_max_f32_e32 v105, 0, v105
	v_max_f32_e32 v106, 0, v106
	v_max_f32_e32 v107, 0, v107
	s_waitcnt lgkmcnt(0)
	global_store_dwordx4 v[220:221], v[212:215], off sc1
	ds_bpermute_b32 v216, v224, v150
	ds_bpermute_b32 v217, v224, v151
	ds_bpermute_b32 v218, v224, v152
	ds_bpermute_b32 v219, v224, v153
	s_mov_b32 s100, 0x20000
	v_lshl_add_u64 v[222:223], v[228:229], 0, s[100:101]
	v_max_f32_e32 v110, 0, v110
	v_max_f32_e32 v111, 0, v111
	v_pk_mul_f32 v[108:109], v[108:109], v[108:109]
	v_pk_mul_f32 v[148:149], v[106:107], v[106:107]
	v_pk_mul_f32 v[106:107], v[104:105], v[104:105]
	v_cvt_pk_bf16_f32 v104, v108, v109
	v_pk_fma_f32 v[98:99], v[130:131], v[158:159], v[98:99] op_sel_hi:[1,0,1]
	v_pk_fma_f32 v[96:97], v[132:133], v[158:159], v[96:97] op_sel_hi:[1,0,1] neg_lo:[1,0,0] neg_hi:[1,0,0]
	v_pk_mul_f32 v[110:111], v[110:111], v[110:111]
	v_pk_fma_f32 v[102:103], v[194:195], v[158:159], v[102:103] op_sel_hi:[1,0,1]
	v_cvt_pk_bf16_f32 v105, v110, v111
	v_cvt_pk_bf16_f32 v106, v106, v107
	v_cvt_pk_bf16_f32 v107, v148, v149
	s_waitcnt lgkmcnt(0)
	global_store_dwordx4 v[222:223], v[216:219], off sc1
	ds_bpermute_b32 v212, v224, v104
	ds_bpermute_b32 v213, v224, v105
	ds_bpermute_b32 v214, v224, v106
	ds_bpermute_b32 v215, v224, v107
	s_mov_b32 s100, 0x40000
	v_lshl_add_u64 v[220:221], v[228:229], 0, s[100:101]
	v_pk_fma_f32 v[100:101], v[128:129], v[158:159], v[100:101] op_sel_hi:[1,0,1] neg_lo:[1,0,0] neg_hi:[1,0,0]
	v_pk_fma_f32 v[98:99], v[158:159], v[98:99], v[142:143] op_sel:[1,0,0]
	v_or_b32_e32 v104, 48, v198
	v_pk_fma_f32 v[96:97], v[158:159], v[96:97], v[140:141] op_sel:[1,0,0]
	v_pk_fma_f32 v[102:103], v[158:159], v[102:103], v[138:139] op_sel:[1,0,0]
	v_pk_fma_f32 v[100:101], v[158:159], v[100:101], v[136:137] op_sel:[1,0,0]
	v_max_f32_e32 v96, 0, v96
	v_max_f32_e32 v97, 0, v97
	v_max_f32_e32 v98, 0, v98
	v_max_f32_e32 v99, 0, v99
	v_ashrrev_i32_e32 v105, 31, v104
	v_pk_fma_f32 v[92:93], v[120:121], v[164:165], v[92:93] op_sel_hi:[1,0,1] neg_lo:[1,0,0] neg_hi:[1,0,0]
	v_max_f32_e32 v100, 0, v100
	v_max_f32_e32 v101, 0, v101
	v_max_f32_e32 v102, 0, v102
	v_max_f32_e32 v103, 0, v103
	v_pk_mul_f32 v[106:107], v[98:99], v[98:99]
	v_pk_mul_f32 v[98:99], v[96:97], v[96:97]
	v_lshlrev_b64 v[104:105], 13, v[104:105]
	v_pk_fma_f32 v[92:93], v[164:165], v[92:93], v[124:125] op_sel:[1,0,0]
	v_pk_mul_f32 v[102:103], v[102:103], v[102:103]
	v_pk_mul_f32 v[100:101], v[100:101], v[100:101]
	v_lshl_add_u64 v[108:109], v[192:193], 0, v[104:105]
	v_cvt_pk_bf16_f32 v96, v100, v101
	v_cvt_pk_bf16_f32 v97, v102, v103
	v_cvt_pk_bf16_f32 v98, v98, v99
	v_cvt_pk_bf16_f32 v99, v106, v107
	v_max_f32_e32 v92, 0, v92
	v_max_f32_e32 v93, 0, v93
	s_waitcnt lgkmcnt(0)
	global_store_dwordx4 v[220:221], v[212:215], off sc1
	ds_bpermute_b32 v216, v224, v96
	ds_bpermute_b32 v217, v224, v97
	ds_bpermute_b32 v218, v224, v98
	ds_bpermute_b32 v219, v224, v99
	s_mov_b32 s100, 0x60000
	v_lshl_add_u64 v[222:223], v[228:229], 0, s[100:101]
	v_pk_fma_f32 v[88:89], v[112:113], v[164:165], v[88:89] op_sel_hi:[1,0,1] neg_lo:[1,0,0] neg_hi:[1,0,0]
	v_pk_fma_f32 v[80:81], v[112:113], v[166:167], v[80:81] op_sel_hi:[1,0,1] neg_lo:[1,0,0] neg_hi:[1,0,0]
	v_pk_mul_f32 v[98:99], v[92:93], v[92:93]
	v_xor_b32_e32 v93, 0x80000000, v115
	v_xor_b32_e32 v92, 0x80000000, v114
	v_xor_b32_e32 v97, 0x80000000, v123
	v_xor_b32_e32 v96, 0x80000000, v122
	v_pk_fma_f32 v[90:91], v[92:93], v[164:165], v[90:91] op_sel_hi:[1,0,1]
	v_pk_fma_f32 v[94:95], v[96:97], v[164:165], v[94:95] op_sel_hi:[1,0,1]
	v_pk_fma_f32 v[90:91], v[164:165], v[90:91], v[118:119] op_sel:[1,0,0]
	v_pk_fma_f32 v[88:89], v[164:165], v[88:89], v[116:117] op_sel:[1,0,0]
	v_pk_fma_f32 v[82:83], v[92:93], v[166:167], v[82:83] op_sel_hi:[1,0,1]
	v_pk_fma_f32 v[94:95], v[164:165], v[94:95], v[126:127] op_sel:[1,0,0]
	v_max_f32_e32 v88, 0, v88
	v_max_f32_e32 v89, 0, v89
	v_max_f32_e32 v90, 0, v90
	v_max_f32_e32 v91, 0, v91
	v_pk_fma_f32 v[86:87], v[96:97], v[166:167], v[86:87] op_sel_hi:[1,0,1]
	v_pk_fma_f32 v[84:85], v[120:121], v[166:167], v[84:85] op_sel_hi:[1,0,1] neg_lo:[1,0,0] neg_hi:[1,0,0]
	v_pk_fma_f32 v[82:83], v[166:167], v[82:83], v[118:119] op_sel:[1,0,0]
	v_pk_fma_f32 v[80:81], v[166:167], v[80:81], v[116:117] op_sel:[1,0,0]
	v_max_f32_e32 v94, 0, v94
	v_max_f32_e32 v95, 0, v95
	v_pk_mul_f32 v[90:91], v[90:91], v[90:91]
	v_pk_mul_f32 v[100:101], v[88:89], v[88:89]
	v_lshl_add_u64 v[102:103], s[46:47], 0, v[134:135]
	v_lshlrev_b64 v[88:89], 1, v[196:197]
	v_pk_fma_f32 v[86:87], v[166:167], v[86:87], v[126:127] op_sel:[1,0,0]
	v_pk_fma_f32 v[84:85], v[166:167], v[84:85], v[124:125] op_sel:[1,0,0]
	v_max_f32_e32 v80, 0, v80
	v_max_f32_e32 v81, 0, v81
	v_max_f32_e32 v82, 0, v82
	v_max_f32_e32 v83, 0, v83
	v_pk_fma_f32 v[74:75], v[92:93], v[156:157], v[74:75] op_sel_hi:[1,0,1]
	v_pk_fma_f32 v[72:73], v[112:113], v[156:157], v[72:73] op_sel_hi:[1,0,1] neg_lo:[1,0,0] neg_hi:[1,0,0]
	v_pk_mul_f32 v[94:95], v[94:95], v[94:95]
	v_lshl_add_u64 v[102:103], v[102:103], 0, v[88:89]
	v_cvt_pk_bf16_f32 v98, v98, v99
	v_cvt_pk_bf16_f32 v99, v94, v95
	v_cvt_pk_bf16_f32 v100, v100, v101
	v_cvt_pk_bf16_f32 v101, v90, v91
	v_max_f32_e32 v84, 0, v84
	v_max_f32_e32 v85, 0, v85
	v_max_f32_e32 v86, 0, v86
	v_max_f32_e32 v87, 0, v87
	v_pk_mul_f32 v[90:91], v[82:83], v[82:83]
	v_pk_mul_f32 v[82:83], v[80:81], v[80:81]
	v_pk_fma_f32 v[78:79], v[96:97], v[156:157], v[78:79] op_sel_hi:[1,0,1]
	v_pk_fma_f32 v[76:77], v[120:121], v[156:157], v[76:77] op_sel_hi:[1,0,1] neg_lo:[1,0,0] neg_hi:[1,0,0]
	v_pk_fma_f32 v[74:75], v[156:157], v[74:75], v[118:119] op_sel:[1,0,0]
	v_pk_fma_f32 v[72:73], v[156:157], v[72:73], v[116:117] op_sel:[1,0,0]
	s_waitcnt lgkmcnt(0)
	global_store_dwordx4 v[222:223], v[216:219], off sc1
	ds_bpermute_b32 v212, v224, v98
	ds_bpermute_b32 v213, v224, v99
	ds_bpermute_b32 v214, v224, v100
	ds_bpermute_b32 v215, v224, v101
	s_mov_b32 s100, 0x100
	v_lshl_add_u64 v[220:221], v[228:229], 0, s[100:101]
	v_pk_mul_f32 v[86:87], v[86:87], v[86:87]
	v_pk_mul_f32 v[84:85], v[84:85], v[84:85]
	v_cvt_pk_bf16_f32 v80, v84, v85
	v_cvt_pk_bf16_f32 v81, v86, v87
	v_pk_fma_f32 v[78:79], v[156:157], v[78:79], v[126:127] op_sel:[1,0,0]
	v_pk_fma_f32 v[76:77], v[156:157], v[76:77], v[124:125] op_sel:[1,0,0]
	v_max_f32_e32 v72, 0, v72
	v_max_f32_e32 v73, 0, v73
	v_max_f32_e32 v74, 0, v74
	v_max_f32_e32 v75, 0, v75
	v_pk_fma_f32 v[66:67], v[92:93], v[158:159], v[66:67] op_sel_hi:[1,0,1]
	v_pk_fma_f32 v[64:65], v[112:113], v[158:159], v[64:65] op_sel_hi:[1,0,1] neg_lo:[1,0,0] neg_hi:[1,0,0]
	v_cvt_pk_bf16_f32 v82, v82, v83
	v_cvt_pk_bf16_f32 v83, v90, v91
	s_waitcnt lgkmcnt(0)
	global_store_dwordx4 v[220:221], v[212:215], off sc1
	ds_bpermute_b32 v216, v224, v80
	ds_bpermute_b32 v217, v224, v81
	ds_bpermute_b32 v218, v224, v82
	ds_bpermute_b32 v219, v224, v83
	s_mov_b32 s100, 0x20100
	v_lshl_add_u64 v[222:223], v[228:229], 0, s[100:101]
	v_max_f32_e32 v76, 0, v76
	v_max_f32_e32 v77, 0, v77
	v_max_f32_e32 v78, 0, v78
	v_max_f32_e32 v79, 0, v79
	v_pk_mul_f32 v[80:81], v[74:75], v[74:75]
	v_pk_mul_f32 v[74:75], v[72:73], v[72:73]
	v_pk_fma_f32 v[66:67], v[158:159], v[66:67], v[118:119] op_sel:[1,0,0]
	v_pk_fma_f32 v[64:65], v[158:159], v[64:65], v[116:117] op_sel:[1,0,0]
	v_pk_mul_f32 v[78:79], v[78:79], v[78:79]
	v_pk_mul_f32 v[76:77], v[76:77], v[76:77]
	v_cvt_pk_bf16_f32 v72, v76, v77
	v_cvt_pk_bf16_f32 v73, v78, v79
	v_pk_fma_f32 v[70:71], v[96:97], v[158:159], v[70:71] op_sel_hi:[1,0,1]
	v_pk_fma_f32 v[68:69], v[120:121], v[158:159], v[68:69] op_sel_hi:[1,0,1] neg_lo:[1,0,0] neg_hi:[1,0,0]
	v_max_f32_e32 v64, 0, v64
	v_max_f32_e32 v65, 0, v65
	v_max_f32_e32 v66, 0, v66
	v_max_f32_e32 v67, 0, v67
	v_cvt_pk_bf16_f32 v74, v74, v75
	v_cvt_pk_bf16_f32 v75, v80, v81
	s_waitcnt lgkmcnt(0)
	global_store_dwordx4 v[222:223], v[216:219], off sc1
	ds_bpermute_b32 v212, v224, v72
	ds_bpermute_b32 v213, v224, v73
	ds_bpermute_b32 v214, v224, v74
	ds_bpermute_b32 v215, v224, v75
	s_mov_b32 s100, 0x40100
	v_lshl_add_u64 v[220:221], v[228:229], 0, s[100:101]
	v_pk_fma_f32 v[70:71], v[158:159], v[70:71], v[126:127] op_sel:[1,0,0]
	v_pk_fma_f32 v[68:69], v[158:159], v[68:69], v[124:125] op_sel:[1,0,0]
	v_pk_mul_f32 v[72:73], v[66:67], v[66:67]
	v_pk_mul_f32 v[66:67], v[64:65], v[64:65]
	v_max_f32_e32 v68, 0, v68
	v_max_f32_e32 v69, 0, v69
	v_max_f32_e32 v70, 0, v70
	v_max_f32_e32 v71, 0, v71
	v_pk_mul_f32 v[70:71], v[70:71], v[70:71]
	v_pk_mul_f32 v[68:69], v[68:69], v[68:69]
	s_nop 0
	v_cvt_pk_bf16_f32 v64, v68, v69
	v_cvt_pk_bf16_f32 v65, v70, v71
	v_cvt_pk_bf16_f32 v66, v66, v67
	v_cvt_pk_bf16_f32 v67, v72, v73
	s_waitcnt lgkmcnt(0)
	global_store_dwordx4 v[220:221], v[212:215], off sc1
	ds_bpermute_b32 v216, v224, v64
	ds_bpermute_b32 v217, v224, v65
	ds_bpermute_b32 v218, v224, v66
	ds_bpermute_b32 v219, v224, v67
	s_mov_b32 s100, 0x60100
	v_lshl_add_u64 v[222:223], v[228:229], 0, s[100:101]
	ds_read2_b64 v[68:71], v207 offset0:128 offset1:144
	ds_read2_b64 v[64:67], v207 offset0:160 offset1:176
	s_mov_b64 s[10:11], 0x120000
	s_waitcnt lgkmcnt(1)
	v_pk_fma_f32 v[58:59], v[130:131], v[68:69], v[58:59] op_sel_hi:[1,0,1]
	v_pk_fma_f32 v[56:57], v[132:133], v[68:69], v[56:57] op_sel_hi:[1,0,1] neg_lo:[1,0,0] neg_hi:[1,0,0]
	v_pk_fma_f32 v[62:63], v[194:195], v[68:69], v[62:63] op_sel_hi:[1,0,1]
	v_pk_fma_f32 v[60:61], v[128:129], v[68:69], v[60:61] op_sel_hi:[1,0,1] neg_lo:[1,0,0] neg_hi:[1,0,0]
	v_pk_fma_f32 v[58:59], v[68:69], v[58:59], v[142:143] op_sel:[1,0,0]
	v_pk_fma_f32 v[56:57], v[68:69], v[56:57], v[140:141] op_sel:[1,0,0]
	v_pk_fma_f32 v[62:63], v[68:69], v[62:63], v[138:139] op_sel:[1,0,0]
	v_pk_fma_f32 v[60:61], v[68:69], v[60:61], v[136:137] op_sel:[1,0,0]
	v_max_f32_e32 v56, 0, v56
	v_max_f32_e32 v57, 0, v57
	v_max_f32_e32 v58, 0, v58
	v_max_f32_e32 v59, 0, v59
	v_pk_fma_f32 v[50:51], v[130:131], v[70:71], v[50:51] op_sel_hi:[1,0,1]
	v_pk_fma_f32 v[48:49], v[132:133], v[70:71], v[48:49] op_sel_hi:[1,0,1] neg_lo:[1,0,0] neg_hi:[1,0,0]
	v_max_f32_e32 v60, 0, v60
	v_max_f32_e32 v61, 0, v61
	v_max_f32_e32 v62, 0, v62
	v_max_f32_e32 v63, 0, v63
	v_pk_mul_f32 v[72:73], v[58:59], v[58:59]
	v_pk_mul_f32 v[58:59], v[56:57], v[56:57]
	v_pk_fma_f32 v[54:55], v[194:195], v[70:71], v[54:55] op_sel_hi:[1,0,1]
	v_pk_fma_f32 v[52:53], v[128:129], v[70:71], v[52:53] op_sel_hi:[1,0,1] neg_lo:[1,0,0] neg_hi:[1,0,0]
	v_pk_fma_f32 v[50:51], v[70:71], v[50:51], v[142:143] op_sel:[1,0,0]
	v_pk_fma_f32 v[48:49], v[70:71], v[48:49], v[140:141] op_sel:[1,0,0]
	v_pk_mul_f32 v[62:63], v[62:63], v[62:63]
	v_pk_mul_f32 v[60:61], v[60:61], v[60:61]
	v_pk_fma_f32 v[54:55], v[70:71], v[54:55], v[138:139] op_sel:[1,0,0]
	v_cvt_pk_bf16_f32 v56, v60, v61
	v_cvt_pk_bf16_f32 v57, v62, v63
	v_cvt_pk_bf16_f32 v58, v58, v59
	v_cvt_pk_bf16_f32 v59, v72, v73
	v_pk_fma_f32 v[52:53], v[70:71], v[52:53], v[136:137] op_sel:[1,0,0]
	v_max_f32_e32 v48, 0, v48
	v_max_f32_e32 v49, 0, v49
	v_max_f32_e32 v50, 0, v50
	v_max_f32_e32 v51, 0, v51
	s_waitcnt lgkmcnt(0)
	v_pk_fma_f32 v[42:43], v[130:131], v[64:65], v[42:43] op_sel_hi:[1,0,1]
	v_pk_fma_f32 v[40:41], v[132:133], v[64:65], v[40:41] op_sel_hi:[1,0,1] neg_lo:[1,0,0] neg_hi:[1,0,0]
	s_waitcnt lgkmcnt(0)
	global_store_dwordx4 v[222:223], v[216:219], off sc1
	ds_bpermute_b32 v212, v224, v56
	ds_bpermute_b32 v213, v224, v57
	ds_bpermute_b32 v214, v224, v58
	ds_bpermute_b32 v215, v224, v59
	s_mov_b32 s100, 0x100000
	v_lshl_add_u64 v[220:221], v[228:229], 0, s[100:101]
	v_max_f32_e32 v52, 0, v52
	v_max_f32_e32 v53, 0, v53
	v_max_f32_e32 v54, 0, v54
	v_max_f32_e32 v55, 0, v55
	v_pk_mul_f32 v[56:57], v[50:51], v[50:51]
	v_pk_mul_f32 v[50:51], v[48:49], v[48:49]
	v_pk_fma_f32 v[46:47], v[194:195], v[64:65], v[46:47] op_sel_hi:[1,0,1]
	v_pk_fma_f32 v[44:45], v[128:129], v[64:65], v[44:45] op_sel_hi:[1,0,1] neg_lo:[1,0,0] neg_hi:[1,0,0]
	v_pk_fma_f32 v[42:43], v[64:65], v[42:43], v[142:143] op_sel:[1,0,0]
	v_pk_fma_f32 v[40:41], v[64:65], v[40:41], v[140:141] op_sel:[1,0,0]
	v_pk_mul_f32 v[54:55], v[54:55], v[54:55]
	v_pk_mul_f32 v[52:53], v[52:53], v[52:53]
	v_cvt_pk_bf16_f32 v48, v52, v53
	v_cvt_pk_bf16_f32 v49, v54, v55
	v_cvt_pk_bf16_f32 v50, v50, v51
	v_cvt_pk_bf16_f32 v51, v56, v57
	v_pk_fma_f32 v[46:47], v[64:65], v[46:47], v[138:139] op_sel:[1,0,0]
	v_pk_fma_f32 v[44:45], v[64:65], v[44:45], v[136:137] op_sel:[1,0,0]
	v_max_f32_e32 v40, 0, v40
	v_max_f32_e32 v41, 0, v41
	v_max_f32_e32 v42, 0, v42
	v_max_f32_e32 v43, 0, v43
	s_mov_b64 s[10:11], 0x140000
	s_waitcnt lgkmcnt(0)
	global_store_dwordx4 v[220:221], v[212:215], off sc1
	ds_bpermute_b32 v216, v224, v48
	ds_bpermute_b32 v217, v224, v49
	ds_bpermute_b32 v218, v224, v50
	ds_bpermute_b32 v219, v224, v51
	s_mov_b32 s100, 0x120000
	v_lshl_add_u64 v[222:223], v[228:229], 0, s[100:101]
	v_max_f32_e32 v44, 0, v44
	v_max_f32_e32 v45, 0, v45
	v_max_f32_e32 v46, 0, v46
	v_max_f32_e32 v47, 0, v47
	v_pk_mul_f32 v[48:49], v[42:43], v[42:43]
	v_pk_mul_f32 v[42:43], v[40:41], v[40:41]
	v_pk_fma_f32 v[38:39], v[194:195], v[66:67], v[38:39] op_sel_hi:[1,0,1]
	v_pk_fma_f32 v[36:37], v[128:129], v[66:67], v[36:37] op_sel_hi:[1,0,1] neg_lo:[1,0,0] neg_hi:[1,0,0]
	v_pk_fma_f32 v[34:35], v[130:131], v[66:67], v[34:35] op_sel_hi:[1,0,1]
	v_pk_fma_f32 v[32:33], v[132:133], v[66:67], v[32:33] op_sel_hi:[1,0,1] neg_lo:[1,0,0] neg_hi:[1,0,0]
	v_pk_mul_f32 v[46:47], v[46:47], v[46:47]
	v_pk_mul_f32 v[44:45], v[44:45], v[44:45]
	v_cvt_pk_bf16_f32 v40, v44, v45
	v_cvt_pk_bf16_f32 v41, v46, v47
	v_cvt_pk_bf16_f32 v42, v42, v43
	v_cvt_pk_bf16_f32 v43, v48, v49
	v_pk_fma_f32 v[38:39], v[66:67], v[38:39], v[138:139] op_sel:[1,0,0]
	v_pk_fma_f32 v[36:37], v[66:67], v[36:37], v[136:137] op_sel:[1,0,0]
	v_pk_fma_f32 v[34:35], v[66:67], v[34:35], v[142:143] op_sel:[1,0,0]
	v_pk_fma_f32 v[32:33], v[66:67], v[32:33], v[140:141] op_sel:[1,0,0]
	s_mov_b64 s[10:11], 0x160000
	v_pk_fma_f32 v[26:27], v[92:93], v[68:69], v[26:27] op_sel_hi:[1,0,1]
	v_pk_fma_f32 v[24:25], v[112:113], v[68:69], v[24:25] op_sel_hi:[1,0,1] neg_lo:[1,0,0] neg_hi:[1,0,0]
	s_waitcnt lgkmcnt(0)
	global_store_dwordx4 v[222:223], v[216:219], off sc1
	ds_bpermute_b32 v212, v224, v40
	ds_bpermute_b32 v213, v224, v41
	ds_bpermute_b32 v214, v224, v42
	ds_bpermute_b32 v215, v224, v43
	s_mov_b32 s100, 0x140000
	v_lshl_add_u64 v[220:221], v[228:229], 0, s[100:101]
	v_max_f32_e32 v36, 0, v36
	v_max_f32_e32 v37, 0, v37
	v_max_f32_e32 v38, 0, v38
	v_max_f32_e32 v39, 0, v39
	v_max_f32_e32 v32, 0, v32
	v_max_f32_e32 v33, 0, v33
	v_max_f32_e32 v34, 0, v34
	v_max_f32_e32 v35, 0, v35
	v_lshl_add_u64 v[42:43], v[134:135], 0, s[10:11]
	v_pk_fma_f32 v[30:31], v[96:97], v[68:69], v[30:31] op_sel_hi:[1,0,1]
	v_pk_fma_f32 v[28:29], v[120:121], v[68:69], v[28:29] op_sel_hi:[1,0,1] neg_lo:[1,0,0] neg_hi:[1,0,0]
	v_pk_fma_f32 v[26:27], v[68:69], v[26:27], v[118:119] op_sel:[1,0,0]
	v_pk_fma_f32 v[24:25], v[68:69], v[24:25], v[116:117] op_sel:[1,0,0]
	v_pk_mul_f32 v[38:39], v[38:39], v[38:39]
	v_pk_mul_f32 v[36:37], v[36:37], v[36:37]
	v_pk_mul_f32 v[40:41], v[34:35], v[34:35]
	v_pk_mul_f32 v[34:35], v[32:33], v[32:33]
	v_cvt_pk_bf16_f32 v32, v36, v37
	v_cvt_pk_bf16_f32 v33, v38, v39
	v_pk_fma_f32 v[30:31], v[68:69], v[30:31], v[126:127] op_sel:[1,0,0]
	v_pk_fma_f32 v[28:29], v[68:69], v[28:29], v[124:125] op_sel:[1,0,0]
	v_max_f32_e32 v24, 0, v24
	v_max_f32_e32 v25, 0, v25
	v_max_f32_e32 v26, 0, v26
	v_max_f32_e32 v27, 0, v27
	v_pk_fma_f32 v[18:19], v[92:93], v[70:71], v[18:19] op_sel_hi:[1,0,1]
	v_pk_fma_f32 v[16:17], v[112:113], v[70:71], v[16:17] op_sel_hi:[1,0,1] neg_lo:[1,0,0] neg_hi:[1,0,0]
	v_cvt_pk_bf16_f32 v34, v34, v35
	v_cvt_pk_bf16_f32 v35, v40, v41
	s_waitcnt lgkmcnt(0)
	global_store_dwordx4 v[220:221], v[212:215], off sc1
	ds_bpermute_b32 v216, v224, v32
	ds_bpermute_b32 v217, v224, v33
	ds_bpermute_b32 v218, v224, v34
	ds_bpermute_b32 v219, v224, v35
	s_mov_b32 s100, 0x160000
	v_lshl_add_u64 v[222:223], v[228:229], 0, s[100:101]
	v_max_f32_e32 v28, 0, v28
	v_max_f32_e32 v29, 0, v29
	v_max_f32_e32 v30, 0, v30
	v_max_f32_e32 v31, 0, v31
	v_pk_mul_f32 v[32:33], v[26:27], v[26:27]
	v_pk_mul_f32 v[26:27], v[24:25], v[24:25]
	v_pk_fma_f32 v[22:23], v[96:97], v[70:71], v[22:23] op_sel_hi:[1,0,1]
	v_pk_fma_f32 v[20:21], v[120:121], v[70:71], v[20:21] op_sel_hi:[1,0,1] neg_lo:[1,0,0] neg_hi:[1,0,0]
	v_pk_fma_f32 v[18:19], v[70:71], v[18:19], v[118:119] op_sel:[1,0,0]
	v_pk_fma_f32 v[16:17], v[70:71], v[16:17], v[116:117] op_sel:[1,0,0]
	v_pk_mul_f32 v[30:31], v[30:31], v[30:31]
	v_pk_mul_f32 v[28:29], v[28:29], v[28:29]
	v_cvt_pk_bf16_f32 v24, v28, v29
	v_cvt_pk_bf16_f32 v25, v30, v31
	v_pk_fma_f32 v[22:23], v[70:71], v[22:23], v[126:127] op_sel:[1,0,0]
	v_pk_fma_f32 v[20:21], v[70:71], v[20:21], v[124:125] op_sel:[1,0,0]
	v_max_f32_e32 v16, 0, v16
	v_max_f32_e32 v17, 0, v17
	v_max_f32_e32 v18, 0, v18
	v_max_f32_e32 v19, 0, v19
	v_pk_fma_f32 v[10:11], v[92:93], v[64:65], v[10:11] op_sel_hi:[1,0,1]
	v_pk_fma_f32 v[8:9], v[112:113], v[64:65], v[8:9] op_sel_hi:[1,0,1] neg_lo:[1,0,0] neg_hi:[1,0,0]
	v_cvt_pk_bf16_f32 v26, v26, v27
	v_cvt_pk_bf16_f32 v27, v32, v33
	s_waitcnt lgkmcnt(0)
	global_store_dwordx4 v[222:223], v[216:219], off sc1
	ds_bpermute_b32 v212, v224, v24
	ds_bpermute_b32 v213, v224, v25
	ds_bpermute_b32 v214, v224, v26
	ds_bpermute_b32 v215, v224, v27
	s_mov_b32 s100, 0x100100
	v_lshl_add_u64 v[220:221], v[228:229], 0, s[100:101]
	v_max_f32_e32 v20, 0, v20
	v_max_f32_e32 v21, 0, v21
	v_max_f32_e32 v22, 0, v22
	v_max_f32_e32 v23, 0, v23
	v_pk_mul_f32 v[24:25], v[18:19], v[18:19]
	v_pk_mul_f32 v[18:19], v[16:17], v[16:17]
	v_pk_fma_f32 v[14:15], v[96:97], v[64:65], v[14:15] op_sel_hi:[1,0,1]
	v_pk_fma_f32 v[12:13], v[120:121], v[64:65], v[12:13] op_sel_hi:[1,0,1] neg_lo:[1,0,0] neg_hi:[1,0,0]
	v_pk_fma_f32 v[10:11], v[64:65], v[10:11], v[118:119] op_sel:[1,0,0]
	v_pk_fma_f32 v[8:9], v[64:65], v[8:9], v[116:117] op_sel:[1,0,0]
	v_pk_mul_f32 v[22:23], v[22:23], v[22:23]
	v_pk_mul_f32 v[20:21], v[20:21], v[20:21]
	v_cvt_pk_bf16_f32 v16, v20, v21
	v_cvt_pk_bf16_f32 v17, v22, v23
	v_pk_fma_f32 v[14:15], v[64:65], v[14:15], v[126:127] op_sel:[1,0,0]
	v_pk_fma_f32 v[12:13], v[64:65], v[12:13], v[124:125] op_sel:[1,0,0]
	v_max_f32_e32 v8, 0, v8
	v_max_f32_e32 v9, 0, v9
	v_max_f32_e32 v10, 0, v10
	v_max_f32_e32 v11, 0, v11
	v_pk_fma_f32 v[2:3], v[92:93], v[66:67], v[2:3] op_sel_hi:[1,0,1]
	v_pk_fma_f32 v[0:1], v[112:113], v[66:67], v[0:1] op_sel_hi:[1,0,1] neg_lo:[1,0,0] neg_hi:[1,0,0]
	v_cvt_pk_bf16_f32 v18, v18, v19
	v_cvt_pk_bf16_f32 v19, v24, v25
	s_waitcnt lgkmcnt(0)
	global_store_dwordx4 v[220:221], v[212:215], off sc1
	ds_bpermute_b32 v216, v224, v16
	ds_bpermute_b32 v217, v224, v17
	ds_bpermute_b32 v218, v224, v18
	ds_bpermute_b32 v219, v224, v19
	s_mov_b32 s100, 0x120100
	v_lshl_add_u64 v[222:223], v[228:229], 0, s[100:101]
	v_max_f32_e32 v12, 0, v12
	v_max_f32_e32 v13, 0, v13
	v_max_f32_e32 v14, 0, v14
	v_max_f32_e32 v15, 0, v15
	v_pk_mul_f32 v[16:17], v[10:11], v[10:11]
	v_pk_mul_f32 v[10:11], v[8:9], v[8:9]
	v_pk_fma_f32 v[2:3], v[66:67], v[2:3], v[118:119] op_sel:[1,0,0]
	v_pk_fma_f32 v[0:1], v[66:67], v[0:1], v[116:117] op_sel:[1,0,0]
	v_pk_mul_f32 v[14:15], v[14:15], v[14:15]
	v_pk_mul_f32 v[12:13], v[12:13], v[12:13]
	v_cvt_pk_bf16_f32 v8, v12, v13
	v_cvt_pk_bf16_f32 v9, v14, v15
	v_pk_fma_f32 v[6:7], v[96:97], v[66:67], v[6:7] op_sel_hi:[1,0,1]
	v_pk_fma_f32 v[4:5], v[120:121], v[66:67], v[4:5] op_sel_hi:[1,0,1] neg_lo:[1,0,0] neg_hi:[1,0,0]
	v_max_f32_e32 v0, 0, v0
	v_max_f32_e32 v1, 0, v1
	v_max_f32_e32 v2, 0, v2
	v_max_f32_e32 v3, 0, v3
	v_cvt_pk_bf16_f32 v10, v10, v11
	v_cvt_pk_bf16_f32 v11, v16, v17
	s_waitcnt lgkmcnt(0)
	global_store_dwordx4 v[222:223], v[216:219], off sc1
	ds_bpermute_b32 v212, v224, v8
	ds_bpermute_b32 v213, v224, v9
	ds_bpermute_b32 v214, v224, v10
	ds_bpermute_b32 v215, v224, v11
	s_mov_b32 s100, 0x140100
	v_lshl_add_u64 v[220:221], v[228:229], 0, s[100:101]
	v_pk_fma_f32 v[6:7], v[66:67], v[6:7], v[126:127] op_sel:[1,0,0]
	v_pk_fma_f32 v[4:5], v[66:67], v[4:5], v[124:125] op_sel:[1,0,0]
	v_pk_mul_f32 v[8:9], v[2:3], v[2:3]
	v_pk_mul_f32 v[2:3], v[0:1], v[0:1]
	v_max_f32_e32 v4, 0, v4
	v_max_f32_e32 v5, 0, v5
	v_max_f32_e32 v6, 0, v6
	v_max_f32_e32 v7, 0, v7
	s_mov_b64 s[10:11], s[42:43]
	v_pk_mul_f32 v[6:7], v[6:7], v[6:7]
	v_pk_mul_f32 v[4:5], v[4:5], v[4:5]
	s_nop 0
	v_cvt_pk_bf16_f32 v0, v4, v5
	v_cvt_pk_bf16_f32 v1, v6, v7
	v_cvt_pk_bf16_f32 v2, v2, v3
	v_cvt_pk_bf16_f32 v3, v8, v9
	s_waitcnt lgkmcnt(0)
	global_store_dwordx4 v[220:221], v[212:215], off sc1
	ds_bpermute_b32 v216, v224, v0
	ds_bpermute_b32 v217, v224, v1
	ds_bpermute_b32 v218, v224, v2
	ds_bpermute_b32 v219, v224, v3
	s_mov_b32 s100, 0x160100
	v_lshl_add_u64 v[222:223], v[228:229], 0, s[100:101]
	s_waitcnt lgkmcnt(0)
	global_store_dwordx4 v[222:223], v[216:219], off sc1
	s_cbranch_vccz .LBB0_1256
	s_waitcnt vmcnt(0)
	s_cmpk_gt_u32 s4, 0xff
	s_cbranch_scc1 .LBB0_1267
	s_barrier
